# MLA: two-chain row sum, grouped fma/exp in PV gaps
# speedup vs baseline: 1.0156x; 1.0006x over previous
; template <int MODE>
; __device__ __forceinline__ void qkt(f32x16& p0, f32x16& p1, const char* Ks, const char* Krs, const char* Qrs, const bf16x8* qr, const i32x8* q8, int r32, int hi) {
;     ...
;     for (int kb = 0; kb < 3; ++kb) {
; #pragma unroll
;       for (int hf = 0; hf < 2; ++hf) { const char* a_ = Ks + (hf * 32 + r32) * 208 + kb * 64 + hi * 32;
;         const u32x4 lo = *reinterpret_cast<const u32x4*>(a_), h4 = *reinterpret_cast<const u32x4*>(a_ + 16);
;         const i32x8 a = {(int)lo.x, (int)lo.y, (int)lo.z, (int)lo.w, (int)h4.x, (int)h4.y, (int)h4.z, (int)h4.w};
;         if (hf) p1 = __builtin_amdgcn_mfma_scale_f32_32x32x64_f8f6f4(a, q8[kb], p1, 0, 0, 0, 0x7F7F7F7F, 0, 0x7F7F7F7F);
;         else p0 = __builtin_amdgcn_mfma_scale_f32_32x32x64_f8f6f4(a, q8[kb], p0, 0, 0, 0, 0x7F7F7F7F, 0, 0x7F7F7F7F); } }
; __device__ __forceinline__ void finishSM8(f32x16& p0, f32x16& p1, float alpha, float& l_reg, bf16x8& pa0, bf16x8& pa1) {
; #pragma unroll
;   for (int r = 0; r < 16; ++r) p1[r] = __builtin_amdgcn_exp2f(p1[r]);
;   float ps = 0;
; #pragma unroll
;   for (int r = 0; r < 16; ++r) ps += p0[r];
; #pragma unroll
;   for (int r = 0; r < 16; ++r) ps += p1[r];
;   { auto rr = __builtin_amdgcn_permlane32_swap(__float_as_uint(ps), __float_as_uint(ps), false, false); ps = __uint_as_float(rr[0]) + __uint_as_float(rr[1]); }
;   l_reg = l_reg * alpha + ps;
.LBB0_655:
	ds_read_b128 v[82:85], v231 offset:49152
	ds_read_b128 v[86:89], v231 offset:49168
	ds_read_b128 v[122:125], v231 offset:49216
	ds_read_b128 v[126:129], v231 offset:49232
	ds_read_b128 v[162:165], v231 offset:49280
	ds_read_b128 v[166:169], v231 offset:49296
	ds_read_b128 v[146:149], v231 offset:55808
	ds_read_b128 v[150:153], v231 offset:55824
	ds_read_b128 v[154:157], v231 offset:55872
	ds_read_b128 v[158:161], v231 offset:55888
	ds_read_b128 v[170:173], v231 offset:55936
	ds_read_b128 v[174:177], v231 offset:55952
	global_load_dwordx4 v[182:185], v[208:209], off
	global_load_dwordx4 v[186:189], v[206:207], off
	s_and_saveexec_b64 s[20:21], s[12:13]
	global_load_dwordx4 v[178:181], v[204:205], off
	s_or_b64 exec, exec, s[20:21]
	v_lshl_add_u64 v[206:207], v[206:207], 0, v[212:213]
	v_lshl_add_u64 v[204:205], v[204:205], 0, v[210:211]
	s_waitcnt lgkmcnt(10)
	v_mfma_scale_f32_32x32x64_f8f6f4 v[82:97], v[82:89], v[114:121], 0, v216, v216 op_sel_hi:[0,0,0]
	v_exp_f32_e32 v240, v98
	v_exp_f32_e32 v242, v99
	v_exp_f32_e32 v239, v100
	v_exp_f32_e32 v241, v101
	v_exp_f32_e32 v245, v102
	v_exp_f32_e32 v246, v103
	v_add_f32_e32 v0, 0, v66
	v_add_f32_e32 v0, v67, v0
	s_waitcnt lgkmcnt(8)
	v_mfma_scale_f32_32x32x64_f8f6f4 v[82:97], v[122:129], v[130:137], v[82:97], v216, v216 op_sel_hi:[0,0,0]
	v_exp_f32_e32 v243, v104
	v_exp_f32_e32 v244, v105
	v_exp_f32_e32 v247, v106
	v_exp_f32_e32 v250, v107
	v_exp_f32_e32 v248, v108
	v_exp_f32_e32 v249, v109
	v_add_f32_e32 v0, v68, v0
	v_add_f32_e32 v236, v242, v240
	v_add_f32_e32 v0, v69, v0
	v_add_f32_e32 v236, v239, v236
	v_add_f32_e32 v236, v241, v236
	s_waitcnt lgkmcnt(6)
	v_mfma_scale_f32_32x32x64_f8f6f4 v[82:97], v[162:169], v[138:145], v[82:97], v216, v216 op_sel_hi:[0,0,0]
	v_exp_f32_e32 v191, v110
	v_exp_f32_e32 v217, v111
	v_exp_f32_e32 v251, v112
	v_exp_f32_e32 v252, v113
	v_add_f32_e32 v0, v70, v0
	v_add_f32_e32 v236, v245, v236
	v_add_f32_e32 v0, v71, v0
	v_add_f32_e32 v236, v246, v236
	v_add_f32_e32 v0, v72, v0
	v_add_f32_e32 v236, v243, v236
	v_add_f32_e32 v0, v73, v0
	v_add_f32_e32 v236, v244, v236
	s_waitcnt lgkmcnt(4)
	v_mfma_scale_f32_32x32x64_f8f6f4 v[98:113], v[146:153], v[114:121], 0, v216, v216 op_sel_hi:[0,0,0]
	v_add_f32_e32 v0, v74, v0
	v_add_f32_e32 v236, v247, v236
	v_add_f32_e32 v0, v75, v0
	v_add_f32_e32 v236, v250, v236
	v_add_f32_e32 v0, v76, v0
	v_add_f32_e32 v236, v248, v236
	v_add_f32_e32 v0, v77, v0
	v_add_f32_e32 v236, v249, v236
	v_add_f32_e32 v0, v78, v0
	v_add_f32_e32 v236, v191, v236
	s_waitcnt lgkmcnt(2)
	v_mfma_scale_f32_32x32x64_f8f6f4 v[98:113], v[154:161], v[130:137], v[98:113], v216, v216 op_sel_hi:[0,0,0]
	v_add_f32_e32 v0, v79, v0
	v_add_f32_e32 v236, v217, v236
	v_add_f32_e32 v0, v80, v0
	v_add_f32_e32 v236, v251, v236
	v_add_f32_e32 v0, v81, v0
	v_add_f32_e32 v236, v252, v236
	v_add_f32_e32 v235, v236, v0
	v_mov_b32_e32 v236, v235
	s_waitcnt lgkmcnt(0)
	v_mfma_scale_f32_32x32x64_f8f6f4 v[98:113], v[170:177], v[138:145], v[98:113], v216, v216 op_sel_hi:[0,0,0]
	s_nop 0
	v_permlane32_swap_b32_e32 v235, v236
	ds_read_b128 v[154:157], v230
	ds_read_b128 v[158:161], v230 offset:16
	ds_read_b128 v[146:149], v230 offset:2560
	ds_read_b128 v[150:153], v230 offset:2576
	ds_read_b128 v[122:125], v230 offset:5120
	ds_read_b128 v[126:129], v230 offset:5136
	ds_read_b128 v[166:169], v230 offset:7696
	v_cvt_pk_fp8_f32 v170, v66, v67
	v_cvt_pk_fp8_f32 v171, v70, v71
	v_cvt_pk_fp8_f32 v172, v74, v75
	v_cvt_pk_fp8_f32 v173, v78, v79
	v_cvt_pk_fp8_f32 v174, v240, v242
	v_cvt_pk_fp8_f32 v175, v245, v246
	v_cvt_pk_fp8_f32 v176, v247, v250
	v_cvt_pk_fp8_f32 v177, v191, v217
	v_cvt_pk_fp8_f32 v170, v68, v69 op_sel:[0,0,1]
	v_cvt_pk_fp8_f32 v171, v72, v73 op_sel:[0,0,1]
	v_cvt_pk_fp8_f32 v172, v76, v77 op_sel:[0,0,1]
	v_cvt_pk_fp8_f32 v173, v80, v81 op_sel:[0,0,1]
	v_cvt_pk_fp8_f32 v174, v239, v241 op_sel:[0,0,1]
	v_cvt_pk_fp8_f32 v175, v243, v244 op_sel:[0,0,1]
	v_cvt_pk_fp8_f32 v176, v248, v249 op_sel:[0,0,1]
	v_cvt_pk_fp8_f32 v177, v251, v252 op_sel:[0,0,1]
	v_max_f32_e32 v0, v83, v83
	v_max_f32_e32 v163, v98, v98
	v_max_f32_e32 v162, v82, v82
	v_max3_f32 v163, v163, v99, v100
	v_max_f32_e32 v0, v162, v0
	v_max3_f32 v163, v163, v101, v102
	v_max3_f32 v0, v0, v84, v85
	v_max3_f32 v163, v163, v103, v104
	v_max3_f32 v0, v0, v86, v87
	v_max3_f32 v163, v163, v105, v106
	v_max3_f32 v0, v0, v88, v89
	v_max3_f32 v163, v163, v107, v108
	v_max3_f32 v0, v0, v90, v91
	v_max3_f32 v163, v163, v109, v110
	v_max3_f32 v0, v0, v92, v93
	v_max3_f32 v163, v163, v111, v112
	v_max3_f32 v0, v0, v94, v95
	v_max_f32_e32 v163, v163, v113
	v_max3_f32 v0, v0, v96, v97
	v_max_f32_e32 v0, v0, v163
	v_mov_b32_e32 v162, v0
	s_nop 1
	v_permlane32_swap_b32_e32 v0, v162
	v_max_f32_e32 v162, v162, v162
	v_max_f32_e32 v0, v0, v0
	v_max_f32_e32 v0, v0, v162
	v_sub_f32_e32 v162, v0, v237
	v_mul_f32_e32 v162, 0x3dd53b94, v162
	v_cmp_ge_f32_e32 vcc, s57, v162
	s_cmp_eq_u64 vcc, exec
	v_max_f32_e32 v162, v237, v237
	s_cselect_b64 vcc, -1, 0
	v_max_f32_e32 v0, v162, v0
	v_cndmask_b32_e32 v238, v0, v237, vcc
	v_sub_f32_e32 v0, v237, v238
	v_mul_f32_e32 v0, 0x3dd53b94, v0
	v_exp_f32_e32 v0, v0
	ds_read_b128 v[162:165], v230 offset:7680
	s_waitcnt lgkmcnt(0)
; #define SBAR() __builtin_amdgcn_sched_barrier(0)
; #define PVC(voff) do { if constexpr (MODE == 0) pv8(o, V_lds + (voff), pa0, pa1, r32, hi); else pv_d0(o, vb0 + (voff), pa0, pa1, pa2, pa3); } while (0)
; #define FSM(P0, P1, AL) do { if constexpr (MODE == 0) finishSM8(P0, P1, AL, l_reg, pa0, pa1); else finishSM(P0, P1, AL, l_reg, pa0, pa1, pa2, pa3); } while (0)
; template <int MODE>
; __device__ __forceinline__ void partialSM(f32x16& p0, f32x16& p1, float& m_reg, float& mn, float& alpha, const float C, int kb, const float* btab, const bool nomask) {
;     ...
;     const float mnC = -mn * C;
; #pragma unroll
;     for (int r = 0; r < 16; ++r) p0[r] = fmaf(p0[r], C, mnC);
; #pragma unroll
;     for (int r = 0; r < 16; ++r) p1[r] = fmaf(p1[r], C, mnC);
; #pragma unroll
;     for (int r = 0; r < 16; ++r) p0[r] = __builtin_amdgcn_exp2f(p0[r]);
; template <int MODE, int SD> ...
;     ...
;   f32x16 pA0, pA1, pB0, pB1; float mnA, mnB, alA, alB; bf16x8 pa0, pa1, pa2 = {}, pa3 = {};
;   const int kbl = kbw - wid * QBLK - r32 + 4 * hi;
;   constexpr int SE = 0, SO = SD - 1;
;   SLOAD(SE, 0); asm volatile("s_waitcnt vmcnt(0)" ::: "memory"); SWRITE(0, SE); __syncthreads();
;   qkt<MODE>(pA0, pA1, K_lds, Kr_lds, Qr_l, qr, q8, r32, hi); partialSM<MODE>(pA0, pA1, m_reg, mnA, alA, C, kbl, btab, nomask);
;   SLOAD(SO, KVBLK); if constexpr (SD == 2) { if (2 < NT) SLOAD(SE, 2 * KVBLK); }
;   SWAIT(); SWRITE(1, SO); __syncthreads();
;   for (int j = 1; j + 1 < NT; j += 2) {
;     SBAR(); qkt<MODE>(pB0, pB1, K_lds + SHM_K, Kr_lds + SHM_KR, Qr_l, qr, q8, r32, hi);
;     FSM(pA0, pA1, alA); SG_QKT(); SBAR();
;     SLOAD(SO, (j + SD) * KVBLK); SBAR();
;     PVC(0); partialSM<MODE>(pB0, pB1, m_reg, mnB, alB, C, kbl + j * KVBLK, btab, nomask); asm volatile("" : "+v"(pB0), "+v"(pB1), "+v"(alB)); SG_PV(); SBAR();
;     __syncthreads(); SWAIT(); SWRITE(0, SE);
;     RESC(alB); __syncthreads();
;     SBAR(); qkt<MODE>(pA0, pA1, K_lds, Kr_lds, Qr_l, qr, q8, r32, hi);
;     FSM(pB0, pB1, alB); SG_QKT(); SBAR();
;     if (SD == 1 || j + 3 < NT) SLOAD(SE, (j + 1 + SD) * KVBLK); SBAR();
;     PVC(SHM_V); partialSM<MODE>(pA0, pA1, m_reg, mnA, alA, C, kbl + (j + 1) * KVBLK, btab, nomask); asm volatile("" : "+v"(pA0), "+v"(pA1), "+v"(alA)); SG_PV(); SBAR();
;     __syncthreads(); SWAIT(); SWRITE(1, SO);
;     RESC(alA); __syncthreads();
	v_mul_f32_e32 v66, 0xbdd53b94, v238
	v_cmp_gt_f32_e32 vcc, 1.0, v0
	s_nop 0
	v_mfma_scale_f32_32x32x64_f8f6f4 v[50:65], v[170:177], v[154:161], v[50:65], v216, v216 op_sel_hi:[0,0,0]
	v_fmamk_f32 v82, v82, 0x3dd53b94, v66
	v_fmamk_f32 v83, v83, 0x3dd53b94, v66
	v_fmamk_f32 v84, v84, 0x3dd53b94, v66
	v_fmamk_f32 v85, v85, 0x3dd53b94, v66
	v_exp_f32_e32 v82, v82
	v_exp_f32_e32 v83, v83
	v_exp_f32_e32 v84, v84
	v_exp_f32_e32 v85, v85
	v_mfma_scale_f32_32x32x64_f8f6f4 v[34:49], v[170:177], v[146:153], v[34:49], v216, v216 op_sel_hi:[0,0,0]
	v_fmamk_f32 v86, v86, 0x3dd53b94, v66
	v_fmamk_f32 v87, v87, 0x3dd53b94, v66
	v_fmamk_f32 v88, v88, 0x3dd53b94, v66
	v_fmamk_f32 v89, v89, 0x3dd53b94, v66
	v_exp_f32_e32 v86, v86
	v_exp_f32_e32 v87, v87
	v_exp_f32_e32 v88, v88
	v_exp_f32_e32 v89, v89
	v_mfma_scale_f32_32x32x64_f8f6f4 v[18:33], v[170:177], v[122:129], v[18:33], v216, v216 op_sel_hi:[0,0,0]
	v_fmamk_f32 v90, v90, 0x3dd53b94, v66
	v_fmamk_f32 v91, v91, 0x3dd53b94, v66
	v_fmamk_f32 v92, v92, 0x3dd53b94, v66
	v_fmamk_f32 v93, v93, 0x3dd53b94, v66
	v_exp_f32_e32 v90, v90
	v_exp_f32_e32 v91, v91
	v_exp_f32_e32 v92, v92
	v_exp_f32_e32 v93, v93
	v_mfma_scale_f32_32x32x64_f8f6f4 v[2:17], v[170:177], v[162:169], v[2:17], v216, v216 op_sel_hi:[0,0,0]
	v_fmamk_f32 v94, v94, 0x3dd53b94, v66
	v_fmamk_f32 v95, v95, 0x3dd53b94, v66
	v_fmamk_f32 v96, v96, 0x3dd53b94, v66
	v_fmamk_f32 v97, v97, 0x3dd53b94, v66
	v_exp_f32_e32 v94, v94
	v_exp_f32_e32 v95, v95
	v_exp_f32_e32 v96, v96
	v_exp_f32_e32 v97, v97
	v_pk_fma_f32 v[98:99], v[98:99], s[78:79], v[66:67] op_sel_hi:[1,0,0]
	v_pk_fma_f32 v[100:101], v[100:101], s[78:79], v[66:67] op_sel_hi:[1,0,0]
	v_pk_fma_f32 v[102:103], v[102:103], s[78:79], v[66:67] op_sel_hi:[1,0,0]
	v_pk_fma_f32 v[104:105], v[104:105], s[78:79], v[66:67] op_sel_hi:[1,0,0]
	v_pk_fma_f32 v[106:107], v[106:107], s[78:79], v[66:67] op_sel_hi:[1,0,0]
	v_pk_fma_f32 v[108:109], v[108:109], s[78:79], v[66:67] op_sel_hi:[1,0,0]
	v_pk_fma_f32 v[110:111], v[110:111], s[78:79], v[66:67] op_sel_hi:[1,0,0]
	v_pk_fma_f32 v[112:113], v[112:113], s[78:79], v[66:67] op_sel_hi:[1,0,0]
	s_cbranch_vccz .LBB0_671
	s_and_saveexec_b64 s[20:21], s[8:9]
	ds_write_b32 v229, v0 offset:128
	s_or_b64 exec, exec, s[20:21]
	s_waitcnt lgkmcnt(0)
	ds_read_b128 v[66:69], v228 offset:224
	ds_read_b128 v[70:73], v228 offset:192
	ds_read_b128 v[74:77], v228 offset:160
	ds_read_b128 v[78:81], v228 offset:128
	s_waitcnt lgkmcnt(3)
	s_nop 7
	v_pk_mul_f32 v[64:65], v[64:65], v[68:69]
	s_waitcnt lgkmcnt(2)
	v_pk_mul_f32 v[60:61], v[60:61], v[72:73]
	s_waitcnt lgkmcnt(1)
	v_pk_mul_f32 v[56:57], v[56:57], v[76:77]
	s_waitcnt lgkmcnt(0)
	v_pk_mul_f32 v[52:53], v[52:53], v[80:81]
	v_pk_mul_f32 v[62:63], v[62:63], v[66:67]
	v_pk_mul_f32 v[58:59], v[58:59], v[70:71]
	v_pk_mul_f32 v[54:55], v[54:55], v[74:75]
	v_pk_mul_f32 v[50:51], v[50:51], v[78:79]
	v_pk_mul_f32 v[48:49], v[48:49], v[68:69]
	v_pk_mul_f32 v[44:45], v[44:45], v[72:73]
	v_pk_mul_f32 v[40:41], v[40:41], v[76:77]
	v_pk_mul_f32 v[36:37], v[36:37], v[80:81]
	v_pk_mul_f32 v[46:47], v[46:47], v[66:67]
	v_pk_mul_f32 v[42:43], v[42:43], v[70:71]
	v_pk_mul_f32 v[38:39], v[38:39], v[74:75]
	v_pk_mul_f32 v[34:35], v[34:35], v[78:79]
	v_pk_mul_f32 v[32:33], v[32:33], v[68:69]
	v_pk_mul_f32 v[28:29], v[28:29], v[72:73]
	v_pk_mul_f32 v[24:25], v[24:25], v[76:77]
	v_pk_mul_f32 v[20:21], v[20:21], v[80:81]
	v_pk_mul_f32 v[30:31], v[30:31], v[66:67]
	v_pk_mul_f32 v[26:27], v[26:27], v[70:71]
	v_pk_mul_f32 v[22:23], v[22:23], v[74:75]
	v_pk_mul_f32 v[18:19], v[18:19], v[78:79]
	v_pk_mul_f32 v[16:17], v[16:17], v[68:69]
	v_pk_mul_f32 v[12:13], v[12:13], v[72:73]
	v_pk_mul_f32 v[8:9], v[8:9], v[76:77]
	v_pk_mul_f32 v[4:5], v[4:5], v[80:81]
	v_pk_mul_f32 v[14:15], v[14:15], v[66:67]
	v_pk_mul_f32 v[10:11], v[10:11], v[70:71]
	v_pk_mul_f32 v[6:7], v[6:7], v[74:75]
	v_pk_mul_f32 v[2:3], v[2:3], v[78:79]
.LBB0_671:
	s_waitcnt vmcnt(0)
	s_waitcnt vmcnt(1)
	ds_write_b128 v225, v[182:185]
	s_waitcnt vmcnt(0)
	ds_write_b128 v226, v[186:189] offset:32768
	s_and_saveexec_b64 s[20:21], s[12:13]
	ds_write_b128 v234, v[178:181] offset:32768
	s_or_b64 exec, exec, s[20:21]
	s_lshl_b32 s26, s25, 6
	s_waitcnt lgkmcnt(0)
	s_barrier
	ds_read_b128 v[66:69], v231 offset:32768
	ds_read_b128 v[70:73], v231 offset:32784
	ds_read_b128 v[122:125], v231 offset:32832
	ds_read_b128 v[126:129], v231 offset:32848
	ds_read_b128 v[162:165], v231 offset:32896
	ds_read_b128 v[166:169], v231 offset:32912
	ds_read_b128 v[146:149], v231 offset:39424
	ds_read_b128 v[150:153], v231 offset:39440
	ds_read_b128 v[154:157], v231 offset:39488
	ds_read_b128 v[158:161], v231 offset:39504
	ds_read_b128 v[170:173], v231 offset:39552
	ds_read_b128 v[174:177], v231 offset:39568
	global_load_dwordx4 v[182:185], v[208:209], off offset:64
	global_load_dwordx4 v[186:189], v[206:207], off
	s_and_saveexec_b64 s[20:21], s[12:13]
	global_load_dwordx4 v[178:181], v[204:205], off
	s_or_b64 exec, exec, s[20:21]
	v_lshl_add_u64 v[206:207], v[206:207], 0, v[212:213]
	v_lshl_add_u64 v[204:205], v[204:205], 0, v[210:211]
	s_waitcnt lgkmcnt(10)
	v_mfma_scale_f32_32x32x64_f8f6f4 v[66:81], v[66:73], v[114:121], 0, v216, v216 op_sel_hi:[0,0,0]
	v_exp_f32_e32 v243, v98
	v_exp_f32_e32 v244, v99
	v_exp_f32_e32 v241, v100
	v_exp_f32_e32 v242, v101
	v_exp_f32_e32 v247, v102
	v_exp_f32_e32 v248, v103
	v_add_f32_e32 v239, 0, v82
	v_add_f32_e32 v239, v83, v239
	s_waitcnt lgkmcnt(8)
	v_mfma_scale_f32_32x32x64_f8f6f4 v[66:81], v[122:129], v[130:137], v[66:81], v216, v216 op_sel_hi:[0,0,0]
	v_exp_f32_e32 v245, v104
	v_exp_f32_e32 v246, v105
	v_exp_f32_e32 v249, v106
	v_exp_f32_e32 v252, v107
	v_exp_f32_e32 v250, v108
	v_exp_f32_e32 v251, v109
	v_add_f32_e32 v239, v84, v239
	v_add_f32_e32 v240, v244, v243
	v_add_f32_e32 v239, v85, v239
	v_add_f32_e32 v240, v241, v240
	v_add_f32_e32 v240, v242, v240
	s_waitcnt lgkmcnt(6)
; template <int MODE>
; __device__ __forceinline__ void partialSM(f32x16& p0, f32x16& p1, float& m_reg, float& mn, float& alpha, const float C, int kb, const float* btab, const bool nomask) {
;     ...
;     float pmax = p0[0];
; #pragma unroll
;     for (int r = 1; r < 16; ++r) pmax = fmaxf(pmax, p0[r]);
; #pragma unroll
;     for (int r = 0; r < 16; ++r) pmax = fmaxf(pmax, p1[r]);
;     { auto rr = __builtin_amdgcn_permlane32_swap(__float_as_uint(pmax), __float_as_uint(pmax), false, false); pmax = fmaxf(__uint_as_float(rr[0]), __uint_as_float(rr[1])); }
;     { const bool keep = __all((pmax - m_reg) * C <= (MODE == 0 ? 7.5f : 11.5f)); mn = keep ? m_reg : fmaxf(m_reg, pmax);   alpha = __builtin_amdgcn_exp2f((m_reg - mn) * C); m_reg = mn; }
;     const float mnC = -mn * C;
; #pragma unroll
;     for (int r = 0; r < 16; ++r) p0[r] = fmaf(p0[r], C, mnC);
; #pragma unroll
;     for (int r = 0; r < 16; ++r) p1[r] = fmaf(p1[r], C, mnC);
; #pragma unroll
;     for (int r = 0; r < 16; ++r) p0[r] = __builtin_amdgcn_exp2f(p0[r]);
; __device__ __forceinline__ void finishSM8(f32x16& p0, f32x16& p1, float alpha, float& l_reg, bf16x8& pa0, bf16x8& pa1) {
; #pragma unroll
;   for (int r = 0; r < 16; ++r) p1[r] = __builtin_amdgcn_exp2f(p1[r]);
;   float ps = 0;
; #pragma unroll
;   for (int r = 0; r < 16; ++r) ps += p0[r];
; #pragma unroll
;   for (int r = 0; r < 16; ++r) ps += p1[r];
;   { auto rr = __builtin_amdgcn_permlane32_swap(__float_as_uint(ps), __float_as_uint(ps), false, false); ps = __uint_as_float(rr[0]) + __uint_as_float(rr[1]); }
;   l_reg = l_reg * alpha + ps;
;   const u32x4 w0 = {pk4_fp8(p0[0], p0[1], p0[2], p0[3]), pk4_fp8(p0[4], p0[5], p0[6], p0[7]), pk4_fp8(p0[8], p0[9], p0[10], p0[11]), pk4_fp8(p0[12], p0[13], p0[14], p0[15])};
;   const u32x4 w1 = {pk4_fp8(p1[0], p1[1], p1[2], p1[3]), pk4_fp8(p1[4], p1[5], p1[6], p1[7]), pk4_fp8(p1[8], p1[9], p1[10], p1[11]), pk4_fp8(p1[12], p1[13], p1[14], p1[15])};
;   pa0 = __builtin_bit_cast(bf16x8, w0); pa1 = __builtin_bit_cast(bf16x8, w1);
; }
; __device__ __forceinline__ void pv8(f32x16* o, const char* Vs, bf16x8 pa0, bf16x8 pa1, int r32, int hi) {
;   const u32x4 a0 = __builtin_bit_cast(u32x4, pa0), a1 = __builtin_bit_cast(u32x4, pa1);
;   const i32x8 P = {(int)a0.x, (int)a0.y, (int)a0.z, (int)a0.w, (int)a1.x, (int)a1.y, (int)a1.z, (int)a1.w};
; #pragma unroll
	v_mfma_scale_f32_32x32x64_f8f6f4 v[66:81], v[162:169], v[138:145], v[66:81], v216, v216 op_sel_hi:[0,0,0]
	v_exp_f32_e32 v254, v110
	v_exp_f32_e32 v191, v111
	v_exp_f32_e32 v253, v112
	v_exp_f32_e32 v217, v113
	v_add_f32_e32 v239, v86, v239
	v_add_f32_e32 v240, v247, v240
	v_add_f32_e32 v239, v87, v239
	v_add_f32_e32 v240, v248, v240
	v_add_f32_e32 v239, v88, v239
	v_add_f32_e32 v240, v245, v240
	v_add_f32_e32 v239, v89, v239
	v_add_f32_e32 v240, v246, v240
	s_waitcnt lgkmcnt(4)
	v_mfma_scale_f32_32x32x64_f8f6f4 v[98:113], v[146:153], v[114:121], 0, v216, v216 op_sel_hi:[0,0,0]
	v_add_f32_e32 v239, v90, v239
	v_add_f32_e32 v240, v249, v240
	v_add_f32_e32 v239, v91, v239
	v_add_f32_e32 v240, v252, v240
	v_add_f32_e32 v239, v92, v239
	v_add_f32_e32 v240, v250, v240
	v_add_f32_e32 v239, v93, v239
	v_add_f32_e32 v240, v251, v240
	v_add_f32_e32 v239, v94, v239
	v_add_f32_e32 v240, v254, v240
	s_waitcnt lgkmcnt(2)
	v_mfma_scale_f32_32x32x64_f8f6f4 v[98:113], v[154:161], v[130:137], v[98:113], v216, v216 op_sel_hi:[0,0,0]
	v_add_f32_e32 v239, v95, v239
	v_add_f32_e32 v240, v191, v240
	v_add_f32_e32 v239, v96, v239
	v_add_f32_e32 v240, v253, v240
	v_add_f32_e32 v239, v97, v239
	v_add_f32_e32 v240, v217, v240
	v_add_f32_e32 v239, v240, v239
	v_mov_b32_e32 v240, v239
	s_waitcnt lgkmcnt(0)
	v_mfma_scale_f32_32x32x64_f8f6f4 v[98:113], v[170:177], v[138:145], v[98:113], v216, v216 op_sel_hi:[0,0,0]
	s_nop 0
	v_permlane32_swap_b32_e32 v239, v240
	ds_read_b128 v[154:157], v230 offset:18432
	ds_read_b128 v[158:161], v230 offset:18448
	ds_read_b128 v[146:149], v230 offset:20992
	ds_read_b128 v[150:153], v230 offset:21008
	ds_read_b128 v[122:125], v230 offset:23552
	ds_read_b128 v[126:129], v230 offset:23568
	ds_read_b128 v[166:169], v230 offset:26128
	v_cvt_pk_fp8_f32 v82, v82, v83
	v_cvt_pk_fp8_f32 v83, v86, v87
	v_cvt_pk_fp8_f32 v82, v84, v85 op_sel:[0,0,1]
	v_cvt_pk_fp8_f32 v83, v88, v89 op_sel:[0,0,1]
	v_cvt_pk_fp8_f32 v84, v90, v91
	v_cvt_pk_fp8_f32 v85, v94, v95
	v_cvt_pk_fp8_f32 v84, v92, v93 op_sel:[0,0,1]
	v_cvt_pk_fp8_f32 v85, v96, v97 op_sel:[0,0,1]
	v_cvt_pk_fp8_f32 v86, v243, v244
	v_cvt_pk_fp8_f32 v87, v247, v248
	v_cvt_pk_fp8_f32 v86, v241, v242 op_sel:[0,0,1]
	v_cvt_pk_fp8_f32 v87, v245, v246 op_sel:[0,0,1]
	v_cvt_pk_fp8_f32 v88, v249, v252
	v_cvt_pk_fp8_f32 v89, v254, v191
	v_cvt_pk_fp8_f32 v88, v250, v251 op_sel:[0,0,1]
	v_cvt_pk_fp8_f32 v89, v253, v217 op_sel:[0,0,1]
	v_max_f32_e32 v162, v67, v67
	v_max_f32_e32 v164, v98, v98
	v_max_f32_e32 v163, v66, v66
	v_max3_f32 v164, v164, v99, v100
	v_max_f32_e32 v162, v163, v162
	v_max3_f32 v164, v164, v101, v102
	v_max3_f32 v162, v162, v68, v69
	v_max3_f32 v164, v164, v103, v104
	v_max3_f32 v162, v162, v70, v71
	v_max3_f32 v164, v164, v105, v106
	v_max3_f32 v162, v162, v72, v73
	v_max3_f32 v164, v164, v107, v108
	v_max3_f32 v162, v162, v74, v75
	v_max3_f32 v164, v164, v109, v110
	v_max3_f32 v162, v162, v76, v77
	v_max3_f32 v164, v164, v111, v112
	v_max3_f32 v162, v162, v78, v79
	v_max_f32_e32 v164, v164, v113
	v_max3_f32 v162, v162, v80, v81
	v_max_f32_e32 v162, v162, v164
	v_mov_b32_e32 v163, v162
	s_nop 1
	v_permlane32_swap_b32_e32 v162, v163
	v_max_f32_e32 v163, v163, v163
	v_max_f32_e32 v162, v162, v162
	v_max_f32_e32 v162, v162, v163
	v_sub_f32_e32 v163, v162, v238
	v_mul_f32_e32 v163, 0x3dd53b94, v163
	v_cmp_ge_f32_e32 vcc, s57, v163
	s_cmp_eq_u64 vcc, exec
	v_max_f32_e32 v163, v238, v238
	s_cselect_b64 vcc, -1, 0
	v_max_f32_e32 v162, v163, v162
	v_cndmask_b32_e32 v237, v162, v238, vcc
	v_sub_f32_e32 v170, v238, v237
	v_mul_f32_e32 v170, 0x3dd53b94, v170
	v_exp_f32_e32 v170, v170
	ds_read_b128 v[162:165], v230 offset:26112
	s_waitcnt lgkmcnt(0)
	v_mul_f32_e32 v172, 0xbdd53b94, v237
	v_cmp_gt_f32_e32 vcc, 1.0, v170
	s_nop 0
	v_mfma_scale_f32_32x32x64_f8f6f4 v[50:65], v[82:89], v[154:161], v[50:65], v216, v216 op_sel_hi:[0,0,0]
	v_fmamk_f32 v66, v66, 0x3dd53b94, v172
	v_fmamk_f32 v67, v67, 0x3dd53b94, v172
	v_fmamk_f32 v68, v68, 0x3dd53b94, v172
	v_fmamk_f32 v69, v69, 0x3dd53b94, v172
	v_exp_f32_e32 v66, v66
	v_exp_f32_e32 v67, v67
	v_exp_f32_e32 v68, v68
	v_exp_f32_e32 v69, v69
	v_mfma_scale_f32_32x32x64_f8f6f4 v[34:49], v[82:89], v[146:153], v[34:49], v216, v216 op_sel_hi:[0,0,0]
	v_fmamk_f32 v70, v70, 0x3dd53b94, v172
	v_fmamk_f32 v71, v71, 0x3dd53b94, v172
	v_fmamk_f32 v72, v72, 0x3dd53b94, v172
	v_fmamk_f32 v73, v73, 0x3dd53b94, v172
	v_exp_f32_e32 v70, v70
	v_exp_f32_e32 v71, v71
	v_exp_f32_e32 v72, v72
	v_exp_f32_e32 v73, v73
	v_mfma_scale_f32_32x32x64_f8f6f4 v[18:33], v[82:89], v[122:129], v[18:33], v216, v216 op_sel_hi:[0,0,0]
	v_fmamk_f32 v74, v74, 0x3dd53b94, v172
	v_fmamk_f32 v75, v75, 0x3dd53b94, v172
	v_fmamk_f32 v76, v76, 0x3dd53b94, v172
	v_fmamk_f32 v77, v77, 0x3dd53b94, v172
	v_exp_f32_e32 v74, v74
	v_exp_f32_e32 v75, v75
	v_exp_f32_e32 v76, v76
	v_exp_f32_e32 v77, v77
	v_mfma_scale_f32_32x32x64_f8f6f4 v[2:17], v[82:89], v[162:169], v[2:17], v216, v216 op_sel_hi:[0,0,0]
	v_fmamk_f32 v78, v78, 0x3dd53b94, v172
	v_fmamk_f32 v79, v79, 0x3dd53b94, v172
	v_fmamk_f32 v80, v80, 0x3dd53b94, v172
	v_fmamk_f32 v81, v81, 0x3dd53b94, v172
	v_exp_f32_e32 v78, v78
	v_exp_f32_e32 v79, v79
	v_exp_f32_e32 v80, v80
	v_exp_f32_e32 v81, v81
	v_pk_fma_f32 v[98:99], v[98:99], s[78:79], v[172:173] op_sel_hi:[1,0,0]
	v_pk_fma_f32 v[100:101], v[100:101], s[78:79], v[172:173] op_sel_hi:[1,0,0]
	v_pk_fma_f32 v[102:103], v[102:103], s[78:79], v[172:173] op_sel_hi:[1,0,0]
	v_pk_fma_f32 v[104:105], v[104:105], s[78:79], v[172:173] op_sel_hi:[1,0,0]
	v_pk_fma_f32 v[106:107], v[106:107], s[78:79], v[172:173] op_sel_hi:[1,0,0]
	v_pk_fma_f32 v[108:109], v[108:109], s[78:79], v[172:173] op_sel_hi:[1,0,0]
	v_pk_fma_f32 v[110:111], v[110:111], s[78:79], v[172:173] op_sel_hi:[1,0,0]
	v_pk_fma_f32 v[112:113], v[112:113], s[78:79], v[172:173] op_sel_hi:[1,0,0]
	s_cbranch_vccz .LBB0_654
	s_and_saveexec_b64 s[20:21], s[8:9]
	s_cbranch_execz .LBB0_653
	ds_write_b32 v229, v170 offset:128
	s_branch .LBB0_653
